# MAIN input-projection GEMM tile order: bits 2 and 4 of the column-tile index swapped (bijection per token tile) so each workgroup's four units mix heavy (gelu/silu) and light (raw/rope) epilogues
# baseline (speedup 1.0000x reference)
; __device__ __forceinline__ unsigned xb_ld(unsigned* p)              { return __hip_atomic_load(p, __ATOMIC_RELAXED, __HIP_MEMORY_SCOPE_AGENT); }
; __device__ __forceinline__ unsigned pk2(float lo, float hi) { return f2bf(lo) | (f2bf(hi) << 16); }
; #define RETID() do { tid = tidx(); lane = tid & 63; wave = tid >> 6; gw = bid * 8 + wave; } while (0)
; __global__ void __launch_bounds__(512, 2) mega(Params p) {
;     ...
;     bool fusedN = (G == 256);
;     { unsigned* bar_ = (unsigned*)(ws + WS_CTL); int nxc = 0;
;       for (int q_ = 0; q_ < 16; ++q_) { const unsigned c_ = xb_ld(&bar_[XB_XCNT(q_)]); if (c_) { ++nxc; if (c_ != 32u || q_ >= 8) fusedN = false; } }
;       if (nxc != 8) fusedN = false; }
;     if (PROBE_DUP == 8) { for (int q_ = 0; q_ < 20; ++q_) GSYNC(); }
;     for (int l = 0; l < 4; ++l) {
;         const float* mod = MOD + (size_t)l * 2 * 6144;
; if (!fusedN || l == 0)
; for (int rep_ = 0; rep_ < (PROBE_DUP == 1 ? 2 : 1); ++rep_) {
;         RETID();
;         { const float* nw = p.in[6] + (size_t)l * DM;
;           for (int row = gw; row < TT; row += ngw) {
;               const float4* xr = (const float4*)(l == 0 ? (row < TL ? p.in[0] + (size_t)row * DM : p.in[2] + (size_t)(row - TL) * DM) : X + (size_t)row * DM) + lane; float4 v[8]; float ss = 0.f;
; #pragma unroll
;               for (int j = 0; j < 8; ++j) { v[j] = xr[64 * j]; ss += v[j].x * v[j].x + v[j].y * v[j].y + v[j].z * v[j].z + v[j].w * v[j].w; }
;               const float r = rsqrtf(wave_sum(ss) * (1.f / DM) + EPS);
;               const float* md = mod + (row >= TL ? 6144 : 0);
;               uint2* hp = (uint2*)(H + (size_t)row * DM) + lane;
; #pragma unroll
;               for (int j = 0; j < 8; ++j) { const int col = 4 * (lane + 64 * j); const float4 w4 = *(const float4*)(nw + col), sc = *(const float4*)(md + 2048 + col), sh = *(const float4*)(md + col);
;                   uint2 o; o.x = pk2(v[j].x * r * w4.x * (1.f + sc.x) + sh.x, v[j].y * r * w4.y * (1.f + sc.y) + sh.y);
;                   o.y = pk2(v[j].z * r * w4.z * (1.f + sc.z) + sh.z, v[j].w * r * w4.w * (1.f + sc.w) + sh.w); hp[64 * j] = o; } } }
;         GSYNC();
; }
;         { pg8::Gemm g{H, WIN + (size_t)l * 8192 * 2048, TT, DIN, DM}; pg8::MainOrder S; S.init(TL, DIN, G, bid);
;           pg8::EpiProj E{P};
;           pg8::gemm_phase<pg8::EpiProj, pg8::MainOrder, true, true>(L, g, S, E); }
.LBB0_41:
	s_or_b64 exec, exec, s[0:1]
	v_mov_b32_e32 v0, 0x22dc0000
	s_barrier
	global_load_dword v1, v0, s[58:59] offset:1280 sc1
	global_load_dword v2, v0, s[58:59] offset:1536 sc1
	global_load_dword v3, v0, s[58:59] offset:1792 sc1
	global_load_dword v4, v0, s[58:59] offset:2048 sc1
	global_load_dword v5, v0, s[58:59] offset:2304 sc1
	global_load_dword v6, v0, s[58:59] offset:2560 sc1
	global_load_dword v7, v0, s[58:59] offset:2816 sc1
	v_mov_b32_e32 v8, 0x22dc1000
	global_load_dword v9, v0, s[58:59] offset:3072 sc1
	global_load_dword v10, v0, s[58:59] offset:3328 sc1
	global_load_dword v11, v0, s[58:59] offset:3584 sc1
	global_load_dword v12, v0, s[58:59] offset:3840 sc1
	global_load_dword v13, v8, s[58:59] sc1
	global_load_dword v14, v8, s[58:59] offset:256 sc1
	global_load_dword v15, v8, s[58:59] offset:512 sc1
	global_load_dword v16, v8, s[58:59] offset:768 sc1
	global_load_dword v17, v8, s[58:59] offset:1024 sc1
	s_add_u32 s88, s58, 0xa000000
	s_addc_u32 s89, s59, 0
	s_add_u32 s40, s58, 0xe200000
	s_addc_u32 s41, s59, 0
	s_add_u32 s78, s58, 0x10300000
	s_addc_u32 s79, s59, 0
	s_add_u32 s24, s58, 0x18808000
	s_addc_u32 s25, s59, 0
	s_add_u32 s0, s58, 0x1a908000
	s_addc_u32 s1, s59, 0
	s_add_u32 s28, s58, 0x1eb08000
	v_writelane_b32 v251, s0, 42
	s_addc_u32 s29, s59, 0
	s_mov_b64 s[94:95], s[58:59]
	v_writelane_b32 v251, s1, 43
	s_add_u32 s0, s58, 0x22d08000
	s_addc_u32 s1, s59, 0
	s_cmpk_eq_i32 s96, 0x100
	s_cselect_b64 s[34:35], -1, 0
	s_mov_b64 s[92:93], s[56:57]
	s_add_u32 s56, s94, 0x22dc0500
	s_addc_u32 s57, s95, 0
	v_writelane_b32 v251, s0, 44
	v_cndmask_b32_e64 v0, 0, 1, s[34:35]
	s_mov_b32 s85, 0
	v_writelane_b32 v251, s1, 45
	s_mov_b64 s[90:91], s[54:55]
	s_mov_b64 s[52:53], s[92:93]
	s_mov_b64 s[54:55], s[94:95]
	s_mov_b32 s43, s85
	s_mul_i32 s97, s97, s96
	s_mul_i32 s97, s97, s23
	v_mov_b32_e32 v165, 0
	v_mov_b32_e32 v179, 0x358637bd
	v_mov_b32_e32 v180, 1
	v_mov_b32_e32 v183, 0x41b17218
	s_movk_i32 s93, 0x4080
	s_movk_i32 s82, 0x6000
	s_mov_b32 s71, 0xffff0000
	s_mov_b32 s73, 0x7f800000
	s_mov_b64 s[76:77], 0x80
	s_mov_b32 s92, 0x3f07dc22
	s_mov_b32 s72, 0x3f35f0e3
	s_mov_b32 s70, 0xbe11a98e
	s_waitcnt vmcnt(15)
	v_cmp_eq_u32_e32 vcc, 32, v1
	s_and_b64 s[30:31], vcc, s[34:35]
	s_waitcnt vmcnt(14)
	v_cmp_ne_u32_e64 s[4:5], 0, v2
	v_cndmask_b32_e64 v8, 0, 1, s[30:31]
	v_cmp_ne_u32_e32 vcc, 0, v1
	v_cmp_eq_u32_e64 s[0:1], 32, v2
	v_cndmask_b32_e64 v2, 0, 1, s[4:5]
	v_cndmask_b32_e32 v0, v0, v8, vcc
	v_addc_co_u32_e32 v1, vcc, 0, v2, vcc
	v_and_b32_e32 v2, 1, v0
	s_add_u32 s58, s94, 0x22dc0600
	v_cmp_eq_u32_e32 vcc, 1, v2
	s_addc_u32 s59, s95, 0
	s_and_b64 s[0:1], s[0:1], vcc
	v_cndmask_b32_e64 v2, 0, 1, s[0:1]
	v_cndmask_b32_e64 v0, v0, v2, s[4:5]
	v_and_b32_e32 v2, 1, v0
	s_waitcnt vmcnt(13)
	v_cmp_eq_u32_e64 s[6:7], 32, v3
	s_add_u32 s30, s94, 0x22dc0700
	v_cmp_eq_u32_e32 vcc, 1, v2
	s_addc_u32 s31, s95, 0
	s_and_b64 s[0:1], s[6:7], vcc
	v_cmp_ne_u32_e64 s[8:9], 0, v3
	v_cndmask_b32_e64 v2, 0, 1, s[0:1]
	s_waitcnt vmcnt(12)
	v_cmp_eq_u32_e64 s[10:11], 32, v4
	v_cndmask_b32_e64 v0, v0, v2, s[8:9]
	v_and_b32_e32 v2, 1, v0
	s_add_u32 s48, s94, 0x22dc0800
	v_cmp_eq_u32_e32 vcc, 1, v2
	s_addc_u32 s49, s95, 0
	s_and_b64 s[0:1], s[10:11], vcc
	v_cndmask_b32_e64 v2, 0, 1, s[0:1]
	v_cmp_ne_u32_e32 vcc, 0, v4
	v_cndmask_b32_e64 v3, 0, 1, s[8:9]
	s_waitcnt vmcnt(11)
	v_cmp_eq_u32_e64 s[12:13], 32, v5
	v_cndmask_b32_e32 v0, v0, v2, vcc
	v_addc_co_u32_e32 v1, vcc, v1, v3, vcc
	v_and_b32_e32 v2, 1, v0
	s_add_u32 s74, s94, 0x22dc0900
	v_cmp_eq_u32_e32 vcc, 1, v2
	s_addc_u32 s75, s95, 0
	s_and_b64 s[0:1], s[12:13], vcc
	v_cmp_ne_u32_e64 s[14:15], 0, v5
	v_cndmask_b32_e64 v2, 0, 1, s[0:1]
	s_add_u32 s0, s94, 0x22dc0a00
	v_cndmask_b32_e64 v0, v0, v2, s[14:15]
	v_and_b32_e32 v2, 1, v0
	s_addc_u32 s1, s95, 0
	s_waitcnt vmcnt(10)
	v_cmp_eq_u32_e64 s[16:17], 32, v6
	v_writelane_b32 v251, s0, 46
	v_cmp_eq_u32_e32 vcc, 1, v2
	v_cndmask_b32_e64 v5, 0, 1, s[14:15]
	v_writelane_b32 v251, s1, 47
	s_and_b64 s[0:1], s[16:17], vcc
	v_cndmask_b32_e64 v2, 0, 1, s[0:1]
	v_cmp_ne_u32_e32 vcc, 0, v6
	s_add_u32 s0, s94, 0x22dc0b00
	s_addc_u32 s1, s95, 0
	v_cndmask_b32_e32 v0, v0, v2, vcc
	v_addc_co_u32_e32 v1, vcc, v1, v5, vcc
	v_and_b32_e32 v2, 1, v0
	s_waitcnt vmcnt(9)
	v_cmp_eq_u32_e64 s[18:19], 32, v7
	v_writelane_b32 v251, s0, 48
	v_cmp_eq_u32_e32 vcc, 1, v2
	v_cmp_ne_u32_e64 s[20:21], 0, v7
	v_writelane_b32 v251, s1, 49
	s_and_b64 s[0:1], s[18:19], vcc
	v_cndmask_b32_e64 v2, 0, 1, s[0:1]
	s_add_u32 s0, s94, 0x22dc0c00
	v_cndmask_b32_e64 v0, v0, v2, s[20:21]
	s_addc_u32 s1, s95, 0
	v_and_b32_e32 v2, 1, v0
	v_writelane_b32 v251, s0, 50
	v_cmp_eq_u32_e32 vcc, 1, v2
	v_cndmask_b32_e64 v7, 0, 1, s[20:21]
	v_writelane_b32 v251, s1, 51
	s_waitcnt vmcnt(8)
	v_cmp_eq_u32_e64 s[0:1], 32, v9
	s_and_b64 s[0:1], s[0:1], vcc
	v_cmp_ne_u32_e32 vcc, 0, v9
	v_cndmask_b32_e64 v2, 0, 1, s[0:1]
	s_add_u32 s0, s94, 0x22dc0d00
	s_addc_u32 s1, s95, 0
	v_cndmask_b32_e32 v0, v0, v2, vcc
	v_writelane_b32 v251, s0, 52
	v_addc_co_u32_e32 v1, vcc, v1, v7, vcc
	v_and_b32_e32 v0, 1, v0
	v_writelane_b32 v251, s1, 53
	s_waitcnt vmcnt(7)
	v_cmp_ne_u32_e64 s[0:1], 0, v10
	v_cmp_eq_u32_e32 vcc, 1, v0
	s_waitcnt vmcnt(0)
; __device__ __forceinline__ unsigned xb_ld(unsigned* p)              { return __hip_atomic_load(p, __ATOMIC_RELAXED, __HIP_MEMORY_SCOPE_AGENT); }
; __device__ __forceinline__ unsigned pk2(float lo, float hi) { return f2bf(lo) | (f2bf(hi) << 16); }
; #define RETID() do { tid = tidx(); lane = tid & 63; wave = tid >> 6; gw = bid * 8 + wave; } while (0)
; __global__ void __launch_bounds__(512, 2) mega(Params p) {
;     ...
;     bool fusedN = (G == 256);
;     { unsigned* bar_ = (unsigned*)(ws + WS_CTL); int nxc = 0;
;       for (int q_ = 0; q_ < 16; ++q_) { const unsigned c_ = xb_ld(&bar_[XB_XCNT(q_)]); if (c_) { ++nxc; if (c_ != 32u || q_ >= 8) fusedN = false; } }
;       if (nxc != 8) fusedN = false; }
;     if (PROBE_DUP == 8) { for (int q_ = 0; q_ < 20; ++q_) GSYNC(); }
;     for (int l = 0; l < 4; ++l) {
;         const float* mod = MOD + (size_t)l * 2 * 6144;
; if (!fusedN || l == 0)
; for (int rep_ = 0; rep_ < (PROBE_DUP == 1 ? 2 : 1); ++rep_) {
;         RETID();
;         { const float* nw = p.in[6] + (size_t)l * DM;
;           for (int row = gw; row < TT; row += ngw) {
;               const float4* xr = (const float4*)(l == 0 ? (row < TL ? p.in[0] + (size_t)row * DM : p.in[2] + (size_t)(row - TL) * DM) : X + (size_t)row * DM) + lane; float4 v[8]; float ss = 0.f;
; #pragma unroll
;               for (int j = 0; j < 8; ++j) { v[j] = xr[64 * j]; ss += v[j].x * v[j].x + v[j].y * v[j].y + v[j].z * v[j].z + v[j].w * v[j].w; }
;               const float r = rsqrtf(wave_sum(ss) * (1.f / DM) + EPS);
;               const float* md = mod + (row >= TL ? 6144 : 0);
;               uint2* hp = (uint2*)(H + (size_t)row * DM) + lane;
; #pragma unroll
;               for (int j = 0; j < 8; ++j) { const int col = 4 * (lane + 64 * j); const float4 w4 = *(const float4*)(nw + col), sc = *(const float4*)(md + 2048 + col), sh = *(const float4*)(md + col);
;                   uint2 o; o.x = pk2(v[j].x * r * w4.x * (1.f + sc.x) + sh.x, v[j].y * r * w4.y * (1.f + sc.y) + sh.y);
;                   o.y = pk2(v[j].z * r * w4.z * (1.f + sc.z) + sh.z, v[j].w * r * w4.w * (1.f + sc.w) + sh.w); hp[64 * j] = o; } } }
;         GSYNC();
; }
;         { pg8::Gemm g{H, WIN + (size_t)l * 8192 * 2048, TT, DIN, DM}; pg8::MainOrder S; S.init(TL, DIN, G, bid);
;           pg8::EpiProj E{P};
;           pg8::gemm_phase<pg8::EpiProj, pg8::MainOrder, true, true>(L, g, S, E); }
	v_or_b32_e32 v2, v17, v16
	v_cndmask_b32_e64 v0, 0, 1, s[0:1]
	s_add_u32 s0, s94, 0x22dc0e00
	s_addc_u32 s1, s95, 0
	v_writelane_b32 v251, s0, 54
	s_nop 1
	v_writelane_b32 v251, s1, 55
	v_cmp_ne_u32_e64 s[0:1], 0, v11
	s_nop 1
	v_addc_co_u32_e64 v0, s[0:1], v1, v0, s[0:1]
	s_add_u32 s0, s94, 0x22dc0f00
	s_addc_u32 s1, s95, 0
	v_writelane_b32 v251, s0, 56
	s_nop 1
	v_writelane_b32 v251, s1, 57
	v_cmp_ne_u32_e64 s[0:1], 0, v12
	s_nop 1
	v_cndmask_b32_e64 v1, 0, 1, s[0:1]
	s_add_u32 s0, s94, 0x22dc1000
	s_addc_u32 s1, s95, 0
	v_writelane_b32 v251, s0, 58
	s_add_u32 s36, s94, 0x22dc1100
	s_addc_u32 s37, s95, 0
	v_writelane_b32 v251, s1, 59
	v_cmp_ne_u32_e64 s[0:1], 0, v13
	s_add_u32 s68, s94, 0x22dc1200
	s_addc_u32 s69, s95, 0
	v_addc_co_u32_e64 v0, s[0:1], v0, v1, s[0:1]
	v_cmp_ne_u32_e64 s[0:1], 0, v14
	s_add_u32 s86, s94, 0x22dc1300
	s_addc_u32 s87, s95, 0
	v_cndmask_b32_e64 v1, 0, 1, s[0:1]
	v_cmp_ne_u32_e64 s[0:1], 0, v15
	s_add_u32 s80, s94, 0x22dc1400
	s_addc_u32 s81, s95, 0
	v_addc_co_u32_e64 v0, s[0:1], v0, v1, s[0:1]
	v_cmp_ne_u32_e64 s[0:1], 0, v16
	s_nop 1
	v_cndmask_b32_e64 v1, 0, 1, s[0:1]
	v_cmp_ne_u32_e64 s[0:1], 0, v17
	s_nop 1
	v_addc_co_u32_e64 v0, s[0:1], v0, v1, s[0:1]
	v_or_b32_e32 v1, v2, v15
	v_or_b32_e32 v1, v1, v14
	v_or_b32_e32 v1, v1, v13
	v_or_b32_e32 v1, v1, v12
	v_or_b32_e32 v1, v1, v11
	v_or_b32_e32 v1, v1, v10
	v_cmp_eq_u32_e64 s[0:1], 0, v1
	v_cmp_eq_u32_e64 s[4:5], 8, v0
	s_and_b64 s[0:1], s[4:5], s[0:1]
	s_and_b64 s[0:1], s[0:1], vcc
	v_writelane_b32 v251, s0, 60
	v_sub_co_u32_e64 v0, s[38:39], s2, 20
	s_nop 0
	v_writelane_b32 v251, s1, 61
	s_xor_b64 s[0:1], s[0:1], -1
	v_writelane_b32 v251, s0, 62
	s_nop 1
	v_writelane_b32 v251, s1, 63
	s_add_u32 s0, s94, 0x22dc0300
	s_addc_u32 s1, s95, 0
	v_writelane_b32 v252, s0, 0
	s_cmp_eq_u32 s22, 15
	v_readlane_b32 s12, v251, 38
	v_writelane_b32 v252, s1, 1
	s_cselect_b64 s[0:1], -1, 0
	v_writelane_b32 v252, s0, 2
	s_cmp_eq_u32 s22, 14
	v_readlane_b32 s13, v251, 39
	v_writelane_b32 v252, s1, 3
	s_cselect_b64 s[0:1], -1, 0
	v_writelane_b32 v252, s0, 4
	s_cmp_eq_u32 s22, 13
	s_nop 0
	v_writelane_b32 v252, s1, 5
	s_cselect_b64 s[0:1], -1, 0
	v_writelane_b32 v252, s0, 6
	s_cmp_eq_u32 s22, 12
	s_nop 0
	v_writelane_b32 v252, s1, 7
	s_cselect_b64 s[0:1], -1, 0
	v_writelane_b32 v252, s0, 8
	s_cmp_eq_u32 s22, 11
	s_nop 0
	v_writelane_b32 v252, s1, 9
	s_cselect_b64 s[0:1], -1, 0
	v_writelane_b32 v252, s0, 10
	s_cmp_eq_u32 s22, 10
	s_nop 0
	v_writelane_b32 v252, s1, 11
	s_cselect_b64 s[0:1], -1, 0
	v_writelane_b32 v252, s0, 12
	s_cmp_eq_u32 s22, 9
	s_nop 0
	v_writelane_b32 v252, s1, 13
	s_cselect_b64 s[0:1], -1, 0
	v_writelane_b32 v252, s0, 14
	s_cmp_eq_u32 s22, 8
	s_nop 0
	v_writelane_b32 v252, s1, 15
	s_cselect_b64 s[0:1], -1, 0
	v_writelane_b32 v252, s0, 16
	s_cmp_eq_u32 s22, 7
	s_nop 0
	v_writelane_b32 v252, s1, 17
	s_cselect_b64 s[0:1], -1, 0
	v_writelane_b32 v252, s0, 18
	s_cmp_eq_u32 s22, 6
	s_nop 0
	v_writelane_b32 v252, s1, 19
	s_cselect_b64 s[0:1], -1, 0
	v_writelane_b32 v252, s0, 20
	s_cmp_eq_u32 s22, 5
	s_nop 0
	v_writelane_b32 v252, s1, 21
	s_cselect_b64 s[0:1], -1, 0
	v_writelane_b32 v252, s0, 22
	s_cmp_eq_u32 s22, 4
	s_nop 0
	v_writelane_b32 v252, s1, 23
	s_cselect_b64 s[0:1], -1, 0
	v_writelane_b32 v252, s0, 24
	s_cmp_eq_u32 s22, 3
	s_nop 0
	v_writelane_b32 v252, s1, 25
	s_cselect_b64 s[0:1], -1, 0
	v_writelane_b32 v252, s0, 26
	s_cmp_eq_u32 s22, 2
	s_nop 0
	v_writelane_b32 v252, s1, 27
	s_cselect_b64 s[0:1], -1, 0
	v_writelane_b32 v252, s0, 28
	s_cmp_eq_u32 s22, 1
	s_nop 0
	v_writelane_b32 v252, s1, 29
	s_cselect_b64 s[0:1], -1, 0
	v_writelane_b32 v252, s0, 30
	s_cmp_eq_u32 s22, 0
	s_nop 0
	v_writelane_b32 v252, s1, 31
	s_cselect_b64 s[0:1], -1, 0
	v_writelane_b32 v252, s0, 32
	s_lshl_b32 s42, s22, 6
	s_nop 0
	v_writelane_b32 v252, s1, 33
	s_lshl_b32 s0, s22, 8
	s_add_u32 s0, s60, s0
	s_addc_u32 s1, s61, 0
	s_add_u32 s4, s0, 0x1400
	s_addc_u32 s5, s1, 0
	v_writelane_b32 v252, s4, 34
	s_add_u32 s0, s0, 0x2400
	s_addc_u32 s1, s1, 0
	v_writelane_b32 v252, s5, 35
	v_writelane_b32 v252, s0, 36
	s_mov_b64 s[60:61], s[30:31]
	s_nop 0
	v_writelane_b32 v252, s1, 37
	s_add_u32 s0, s94, 0x22dc3500
	s_addc_u32 s1, s95, 0
	v_writelane_b32 v252, s0, 38
	s_nop 1
	v_writelane_b32 v252, s1, 39
	s_add_u32 s0, s94, 0x22dc3600
	s_addc_u32 s1, s95, 0
	v_writelane_b32 v252, s0, 40
	s_cmpk_lt_i32 s2, 0x400
	s_nop 0
	v_writelane_b32 v252, s1, 41
	s_cselect_b64 s[0:1], -1, 0
	v_writelane_b32 v252, s0, 42
	s_ashr_i32 s3, s2, 31
	s_nop 0
	v_writelane_b32 v252, s1, 43
	s_lshr_b32 s0, s3, 29
	s_add_i32 s0, s2, s0
	s_ashr_i32 s11, s0, 3
	s_and_b32 s0, s0, -8
	s_sub_i32 s16, s2, s0
	s_lshl_b32 s17, s16, 7
	s_ashr_i32 s0, s96, 31
	v_writelane_b32 v252, s0, 44
	s_add_u32 s0, s94, 0x22dc3800
	v_writelane_b32 v252, s0, 45
	s_addc_u32 s0, s95, 0
	s_cmp_gt_i32 s2, 31
	v_writelane_b32 v252, s0, 46
	s_cselect_b64 s[0:1], -1, 0
	v_writelane_b32 v252, s0, 47
	s_nop 1
	v_writelane_b32 v252, s1, 48
	s_sub_i32 s0, s2, 32
	v_writelane_b32 v252, s0, 49
	s_cmpk_lt_i32 s2, 0x338
	v_readfirstlane_b32 s0, v0
	s_cselect_b64 s[4:5], -1, 0
	s_lshr_b32 s0, s0, 2
	v_writelane_b32 v252, s4, 50
	s_sub_i32 s20, 31, s0
	s_and_b32 s0, s2, 3
	v_writelane_b32 v252, s5, 51
	s_or_b32 s21, s0, 28
	s_sub_i32 s0, s96, 32
	s_add_i32 s27, s2, 12
	s_add_i32 s30, s2, 6
	v_writelane_b32 v252, s0, 52
	s_add_u32 s0, s94, 0x22dc3700
	v_writelane_b32 v252, s0, 53
	s_addc_u32 s0, s95, 0
	v_writelane_b32 v252, s0, 54
	s_lshl_b32 s0, s2, 9
	s_lshl_b32 s65, s96, 9
	v_writelane_b32 v252, s0, 55
	s_cmp_gt_i32 s96, 31
	s_movk_i32 s0, 0x410
	s_cselect_b32 s0, s0, 0x420
	s_cmp_lt_i32 s2, s0
	v_writelane_b32 v252, s0, 56
	s_cselect_b64 s[0:1], -1, 0
;     __device__ bool next(int i, Unit& u) const { if (i != 0) return false; u.pm = pm; u.pn = pn; return true; }
; #define RETID() do { tid = tidx(); lane = tid & 63; wave = tid >> 6; gw = bid * 8 + wave; } while (0)
;     __device__ bool next(int i, Unit& u) const {
;         if (!StaticOrder::next(i, u)) return false;
;         if (u.pn >= 28 && u.pm >= 29) { const int j = (31 - u.pm) * 4 + (u.pn - 28); u.pm = 32; u.pn = (j < 6) ? j : 8 + (j - 6); }
;         return true;
; __global__ void __launch_bounds__(512, 2) mega(Params p) {
;     ...
;         { const float lam = LAM[l], li1 = 1.f - LAM[4 + l]; const float* sw = p.in[15] + (size_t)l * 256;
;           const int nrow = (l < 3) ? TT : TL;
;           const bool side = (l < 3) && (G >= 32);
;           const int apn = side ? (G - 16) * 8 : ngw;
;           if (side && bid >= G - 16) { RETID(); const int r = 512 + (bid - (G - 16)); hgrn_c_item(P, LB + (size_t)l * 512, LB + (size_t)(4 + l) * 512, ST, p.in[13] + (size_t)l * 128, Y, r >> 2, r & 3, L, tid); }
	v_writelane_b32 v252, s0, 57
	s_cmp_lt_i32 s96, 32
	v_mbcnt_lo_u32_b32 v0, -1, 0
	v_writelane_b32 v252, s1, 58
	s_cselect_b64 s[0:1], -1, 0
	v_writelane_b32 v252, s0, 59
	v_mbcnt_hi_u32_b32 v171, -1, v0
	v_and_b32_e32 v0, 64, v171
	v_writelane_b32 v252, s1, 60
	s_add_i32 s0, s62, 0xffffff80
	v_writelane_b32 v252, s0, 61
	s_add_i32 s0, s96, -16
	s_cmp_lt_i32 s2, s0
	s_cselect_b64 s[4:5], -1, 0
	s_sub_i32 s0, s2, s0
	v_writelane_b32 v252, s4, 62
	s_add_i32 s1, s0, 0x200
	v_add_u32_e32 v172, 64, v0
	v_writelane_b32 v252, s5, 63
	s_lshr_b32 s4, s1, 2
	s_and_b32 s5, s0, 3
	s_lshl_b32 s0, s4, 6
	s_lshl_b32 s6, s5, 7
	s_lshl_b32 s9, s5, 8
	v_writelane_b32 v253, s0, 0
	s_add_u32 s0, s78, s9
	s_addc_u32 s1, s79, 0
	v_writelane_b32 v253, s0, 1
	v_xor_b32_e32 v178, 1, v171
	v_xor_b32_e32 v177, 2, v171
	v_writelane_b32 v253, s1, 2
	s_lshl_b32 s0, s5, 9
	s_add_u32 s0, s12, s0
	v_writelane_b32 v253, s0, 3
	s_addc_u32 s0, s13, 0
	s_add_i32 s84, s4, 0xffffff80
	v_writelane_b32 v253, s0, 4
	s_lshl_b64 s[0:1], s[84:85], 18
	s_add_u32 s0, s28, s0
	s_addc_u32 s1, s29, s1
	s_lshl_b32 s5, s5, 16
	s_add_u32 s0, s0, s5
	v_writelane_b32 v253, s2, 5
	s_addc_u32 s1, s1, 0
	v_readlane_b32 s83, v253, 5
	v_writelane_b32 v253, s0, 6
	s_add_u32 s5, s28, s5
	s_addc_u32 s7, s29, 0
	v_writelane_b32 v253, s1, 7
	s_sub_i32 s0, 0x107, s4
	s_ashr_i32 s1, s0, 31
	s_lshl_b64 s[0:1], s[0:1], 18
	s_add_u32 s0, s5, s0
	s_addc_u32 s1, s7, s1
	v_writelane_b32 v253, s0, 8
	s_cmpk_lt_i32 s83, 0x100
	s_mov_b32 s84, s3
	v_writelane_b32 v253, s1, 9
	s_cselect_b64 s[0:1], -1, 0
	v_writelane_b32 v253, s0, 10
	v_readlane_b32 s2, v251, 34
	v_readlane_b32 s3, v251, 35
	v_writelane_b32 v253, s1, 11
	s_add_u32 s0, s94, 0xe000000
	v_writelane_b32 v253, s0, 12
	s_addc_u32 s0, s95, 0
	v_writelane_b32 v253, s0, 13
	s_add_u32 s0, s94, 0x22dc7c00
	v_writelane_b32 v253, s0, 14
	s_addc_u32 s0, s95, 0
	v_writelane_b32 v253, s0, 15
	s_lshl_b32 s0, s22, 2
	s_ashr_i32 s8, s26, 3
	s_add_i32 s12, s8, s0
	s_ashr_i32 s13, s12, 31
	s_and_b32 s19, s26, 7
	s_lshl_b32 s18, s16, 5
	s_lshl_b32 s10, s19, 20
	s_lshl_b64 s[0:1], s[12:13], 20
	s_add_u32 s2, s2, s10
	v_writelane_b32 v253, s2, 16
	s_addc_u32 s2, s3, 0
	s_add_u32 s14, s24, s0
	s_addc_u32 s15, s25, s1
	v_writelane_b32 v253, s2, 17
	s_add_u32 s2, s14, 0x80000
	s_addc_u32 s3, s15, 0
	v_writelane_b32 v253, s2, 18
	v_xor_b32_e32 v176, 4, v171
	s_movk_i32 s4, 0x20ff
	v_writelane_b32 v253, s3, 19
	s_lshl_b32 s2, s12, 8
	s_lshl_b32 s3, s19, 8
	s_cmp_gt_i32 s12, 31
	v_writelane_b32 v253, s3, 20
	s_cselect_b32 s7, 0x1800, 0
	s_add_u32 s3, s94, 0x22dcd000
	v_writelane_b32 v253, s3, 21
	s_addc_u32 s3, s95, 0
	v_writelane_b32 v253, s3, 22
	s_lshl_b32 s3, s12, 6
	s_lshl_b32 s12, s19, 5
	v_writelane_b32 v253, s3, 23
	s_or_b32 s13, s2, s12
	v_writelane_b32 v253, s2, 24
	s_or_b32 s2, s13, 24
	s_cmp_lt_i32 s26, 4
	v_writelane_b32 v253, s2, 25
	s_cselect_b64 s[2:3], -1, 0
	s_lshl_b32 s13, s26, 3
	s_lshl_b32 s19, s22, 5
	v_writelane_b32 v253, s2, 26
	s_add_i32 s13, s13, s19
	s_mul_i32 s19, s16, 0x81
	v_writelane_b32 v253, s3, 27
	s_add_i32 s2, s13, 0x2000
	s_cmp_lt_i32 s16, 0
	s_cselect_b32 s17, s19, s17
	s_mul_i32 s16, s16, 33
	s_cselect_b32 s26, s16, s18
	s_add_i32 s16, s17, s11
	s_ashr_i32 s17, s16, 31
	s_lshr_b32 s17, s17, 24
	s_add_i32 s17, s16, s17
	s_and_b32 s18, s17, 0xffffff00
	s_sub_i32 s16, s16, s18
	s_bfe_u32 s18, s16, 0x3001c
	s_add_i32 s18, s16, s18
	s_and_b32 s19, s18, 0xfff8
	s_ashr_i32 s17, s17, 8
	s_sub_i32 s19, s16, s19
	s_lshl_b32 s17, s17, 3
	s_sext_i32_i16 s19, s19
	s_add_i32 s31, s17, s19
	s_sext_i32_i16 s17, s18
	s_ashr_i32 s33, s17, 3
	s_lshr_b32 s18, s33, 2
	s_lshr_b32 s19, s33, 4
	s_xor_b32 s18, s18, s19
	s_and_b32 s18, s18, 1
	s_mul_i32 s18, s18, 20
	s_xor_b32 s33, s33, s18
	s_cmp_gt_i32 s33, 27
	s_cselect_b64 s[16:17], -1, 0
	s_cmp_gt_i32 s31, 28
	s_cselect_b64 s[18:19], -1, 0
	s_and_b64 s[16:17], s[16:17], s[18:19]
	s_lshl_b32 s18, s31, 2
	s_sub_i32 s18, s33, s18
	v_writelane_b32 v253, s2, 28
	s_cmpk_lt_i32 s18, 0xffa6
	s_movk_i32 s2, 0x60
	s_cselect_b32 s19, s2, 0x62
	s_add_i32 s19, s19, s18
	s_and_b64 s[16:17], s[16:17], exec
	s_cselect_b32 s46, s19, s33
	s_cselect_b32 s50, 32, s31
	s_and_b64 s[2:3], s[38:39], exec
	s_cselect_b32 s2, s27, s21
	s_cmp_lt_i32 s83, 2
	s_cselect_b32 s2, s30, s2
	s_cmp_lt_i32 s83, 20
	s_cselect_b32 s16, 32, s20
	s_cselect_b32 s17, 0, 3
	s_ashr_i32 s3, s2, 31
	s_lshl_b32 s18, s16, 20
	s_lshl_b64 s[20:21], s[2:3], 20
	s_add_u32 s30, s40, s18
	s_addc_u32 s31, s41, 0
	s_add_u32 s38, s30, 0x80000
	s_addc_u32 s39, s31, 0
	v_writelane_b32 v253, s38, 29
	s_lshl_b32 s3, s2, 8
	s_lshl_b32 s2, s2, 1
	v_writelane_b32 v253, s39, 30
	s_mov_b32 s38, 0x20002211
	s_and_b32 s2, s2, -4
	s_mov_b32 s39, 0x22003333
	v_writelane_b32 v253, s3, 31
	s_lshr_b64 s[2:3], s[38:39], s2
	s_and_b32 s2, s2, 3
	s_lshl_b32 s3, s16, 8
	s_cmp_eq_u32 s2, 3
	s_cselect_b32 s2, s17, s2
	v_writelane_b32 v253, s3, 32
	s_cmp_eq_u32 s2, 3
	v_writelane_b32 v253, s2, 33
	s_cselect_b64 s[2:3], -1, 0
	v_writelane_b32 v253, s2, 34
	s_movk_i32 s33, 0x90
;     __device__ bool next(int i, Unit& u) const { if (i != 0) return false; u.pm = pm; u.pn = pn; return true; }
;     __host__ __device__ bool next(int i, Unit& u) const {
;         const long L = (long)i * G + c; if (L >= nwg) return false;
;         int wgid = (int)L; { const int q = nwg / NXCD, r = nwg % NXCD, xcd = wgid % NXCD, off = wgid / NXCD; wgid = (xcd < r ? xcd * (q + 1) : r * (q + 1) + (xcd - r) * q) + off; }
;         const int nig = WGM * nN, gid = wgid / nig, fm = gid * WGM, gsz = (nM - fm) < WGM ? (nM - fm) : WGM;
;         u.pm = fm + ((wgid % nig) % gsz); u.pn = (wgid % nig) / gsz; return true;
; __global__ void __launch_bounds__(512, 2) mega(Params p) {
;     ...
;         else
;         { const int M2 = TL;
;           pg8::Gemm g{Y, WOUT + (size_t)l * 2048 * 2048, M2, DM, DM}; pg8::StaticOrder S; S.init(M2, DM, G, bid);
;           pg8::EpiOut E{X, l == 0 ? p.in[0] : X, mod};
;           pg8::gemm_phase<pg8::EpiOut, pg8::StaticOrder, true, true>(L, g, S, E); }
	s_mov_b32 s27, 0x3f317217
	v_writelane_b32 v253, s3, 35
	s_add_i32 s2, s26, s11
	s_ashr_i32 s3, s2, 31
	s_lshr_b32 s3, s3, 26
	s_add_i32 s3, s2, s3
	s_and_b32 s11, s3, 0xffc0
	s_sub_i32 s2, s2, s11
	s_bfe_i32 s11, s2, 0x80000
	s_bfe_u32 s11, s11, 0x3000c
	s_add_i32 s11, s2, s11
	s_and_b32 s16, s11, 0xf8
	s_sub_i32 s2, s2, s16
	s_ashr_i32 s3, s3, 6
	s_bfe_i32 s11, s11, 0x80000
	s_lshl_b32 s3, s3, 3
	s_sext_i32_i16 s11, s11
	s_sext_i32_i8 s2, s2
	s_add_i32 s16, s3, s2
	s_ashr_i32 s2, s11, 3
	v_writelane_b32 v253, s2, 36
	s_lshr_b32 s2, s11, 3
	s_bfe_i64 s[2:3], s[2:3], 0x100000
	s_lshl_b64 s[2:3], s[2:3], 20
	v_writelane_b32 v253, s2, 37
	s_ashr_i32 s17, s16, 31
	s_mov_b32 s26, 0x3e027906
	v_writelane_b32 v253, s3, 38
	s_mov_b32 s2, s16
	v_writelane_b32 v253, s2, 39
	s_nop 1
	v_writelane_b32 v253, s3, 40
	s_lshl_b64 s[2:3], s[16:17], 20
	s_add_u32 s2, s24, s2
	s_addc_u32 s3, s25, s3
	s_add_u32 s16, s2, 0x80000
	v_writelane_b32 v253, s2, 41
	s_addc_u32 s17, s3, 0
	s_ashr_i32 s47, s46, 31
	v_writelane_b32 v253, s3, 42
	v_writelane_b32 v253, s16, 43
	s_mov_b32 s2, s50
	s_ashr_i32 s51, s50, 31
	v_writelane_b32 v253, s17, 44
	v_writelane_b32 v253, s2, 45
	s_mov_b32 s16, s46
	s_nop 0
	v_writelane_b32 v253, s3, 46
	v_writelane_b32 v253, s16, 47
	s_lshl_b64 s[2:3], s[50:51], 20
	s_mov_b64 s[50:51], s[90:91]
	v_writelane_b32 v253, s17, 48
	s_lshl_b64 s[16:17], s[46:47], 20
	v_writelane_b32 v253, s16, 49
	s_add_u32 s2, s40, s2
	s_movk_i32 s47, 0x1000
	v_writelane_b32 v253, s17, 50
	v_writelane_b32 v253, s40, 51
	s_addc_u32 s3, s41, s3
	s_add_u32 s16, s2, 0x80000
	v_writelane_b32 v253, s41, 52
	v_writelane_b32 v253, s2, 53
	s_addc_u32 s17, s3, 0
	s_mov_b32 s91, 0x800000
	v_writelane_b32 v253, s3, 54
	v_writelane_b32 v253, s16, 55
	s_add_u32 s2, s24, s9
	s_addc_u32 s3, s25, 0
	v_writelane_b32 v253, s17, 56
	v_writelane_b32 v253, s2, 57
	s_ashr_i32 s67, s66, 31
	s_ashr_i32 s63, s62, 31
	v_writelane_b32 v253, s3, 58
	v_writelane_b32 v253, s66, 59
	s_lshl_b64 s[2:3], s[62:63], 13
	s_mov_b32 s90, 0x3e6d3388
	v_writelane_b32 v253, s67, 60
	v_writelane_b32 v253, s2, 61
	s_movk_i32 s67, 0x3000
	s_mov_b32 s66, 0x20000
	v_writelane_b32 v253, s3, 62
	s_add_u32 s2, s94, s18
	s_addc_u32 s3, s95, 0
	v_writelane_b32 v253, s2, 63
	s_add_u32 s2, s2, 0xe280080
	v_writelane_b32 v254, s3, 0
	s_addc_u32 s3, s3, 0
	v_writelane_b32 v254, s2, 1
	s_nop 1
	v_writelane_b32 v254, s3, 2
	s_add_u32 s2, s94, s20
	v_writelane_b32 v254, s20, 3
	s_addc_u32 s3, s95, s21
	s_add_u32 s2, s2, 0x100
	v_writelane_b32 v254, s21, 4
	v_writelane_b32 v254, s2, 5
	s_addc_u32 s2, s3, 0
	v_writelane_b32 v254, s2, 6
	s_add_u32 s2, s94, 0x10302810
	s_addc_u32 s3, s95, 0
	v_writelane_b32 v254, s2, 7
	s_nop 1
	v_writelane_b32 v254, s3, 8
	s_lshl_b32 s2, s83, 11
	v_writelane_b32 v254, s2, 9
	s_lshl_b32 s2, s83, 5
	v_writelane_b32 v254, s2, 10
	s_lshl_b32 s2, s96, 5
	s_add_u32 s0, s94, s0
	v_writelane_b32 v254, s2, 11
	s_addc_u32 s1, s95, s1
	v_writelane_b32 v254, s0, 12
	s_add_u32 s0, s0, 0x18888080
	v_writelane_b32 v254, s1, 13
	s_addc_u32 s1, s1, 0
	v_writelane_b32 v254, s0, 14
	s_mul_hi_i32 s3, s62, 0x4080
	s_mul_i32 s2, s62, 0x4080
	v_writelane_b32 v254, s1, 15
	v_writelane_b32 v254, s48, 16
	s_add_u32 s0, s94, s10
	s_addc_u32 s1, s95, 0
	v_writelane_b32 v254, s49, 17
	v_writelane_b32 v254, s50, 18
	v_writelane_b32 v254, s51, 19
	v_writelane_b32 v254, s52, 20
	v_writelane_b32 v254, s53, 21
	v_writelane_b32 v254, s54, 22
	v_writelane_b32 v254, s55, 23
	v_writelane_b32 v254, s42, 24
	s_add_u32 s16, s0, 0x8000100
	s_addc_u32 s17, s1, 0
	v_writelane_b32 v254, s43, 25
	s_lshl_b32 s0, s22, 10
	s_lshl_b32 s1, s8, 8
	v_writelane_b32 v254, s2, 26
	s_add_i32 s0, s0, s1
	s_add_i32 s1, s13, 0x1ff8
	v_writelane_b32 v254, s3, 27
	v_writelane_b32 v254, s1, 28
	s_xor_b64 s[2:3], s[34:35], -1
	v_writelane_b32 v254, s2, 29
	s_lshl_b32 s1, s7, 2
	s_or_b32 s0, s0, s12
	v_writelane_b32 v254, s3, 30
	v_writelane_b32 v254, s1, 31
	v_writelane_b32 v254, s0, 32
	s_add_i32 s0, s0, -8
	v_writelane_b32 v254, s0, 33
	s_add_i32 s0, 0, 0x23ff4
	v_writelane_b32 v254, s0, 34
	s_add_i32 s0, 0, 0x13200
	v_writelane_b32 v254, s0, 35
	s_add_i32 s0, 0, 0x19e00
	v_writelane_b32 v254, s0, 36
	s_add_i32 s0, 0, 0x22600
	v_writelane_b32 v254, s0, 37
	s_lshl_b32 s0, s6, 1
	v_writelane_b32 v254, s0, 38
	s_add_i32 s5, 0, 0x23ff0
	s_movk_i32 s95, 0x2000
	v_writelane_b32 v254, s1, 39
	v_writelane_b32 v254, s62, 40
	s_movk_i32 s3, 0x7fff
	s_movk_i32 s8, 0x110
	v_writelane_b32 v254, s63, 41
	v_writelane_b32 v254, s56, 42
	s_add_i32 s9, 0, 0x17a00
	s_movk_i32 s10, 0x1100
	v_writelane_b32 v254, s57, 43
	v_writelane_b32 v254, s58, 44
	s_mov_b32 s94, 0xbf3a00e3
	s_mov_b32 s2, 0xbf38aa3b
	v_writelane_b32 v254, s59, 45
	v_writelane_b32 v254, s60, 46
	s_mov_b32 s12, s85
	s_nop 0
	v_writelane_b32 v254, s61, 47
	v_writelane_b32 v254, s48, 48
	s_nop 1
	v_writelane_b32 v254, s49, 49
	v_writelane_b32 v254, s74, 50
	s_nop 1
	v_writelane_b32 v254, s75, 51
	v_writelane_b32 v254, s65, 52
	v_writelane_b32 v254, s5, 53
	v_writelane_b32 v254, s84, 54
	s_branch .LBB0_44

;     __device__ bool next(int i, Unit& u) const { if (i != 0) return false; u.pm = pm; u.pn = pn; return true; }
;     __host__ __device__ bool next(int i, Unit& u) const {
;         const long L = (long)i * G + c; if (L >= nwg) return false;
;         int wgid = (int)L; { const int q = nwg / NXCD, r = nwg % NXCD, xcd = wgid % NXCD, off = wgid / NXCD; wgid = (xcd < r ? xcd * (q + 1) : r * (q + 1) + (xcd - r) * q) + off; }
;         const int nig = WGM * nN, gid = wgid / nig, fm = gid * WGM, gsz = (nM - fm) < WGM ? (nM - fm) : WGM;
;         u.pm = fm + ((wgid % nig) % gsz); u.pn = (wgid % nig) / gsz; return true;
;     __device__ bool next(int i, Unit& u) const {
;         if (!StaticOrder::next(i, u)) return false;
;         if (u.pn >= 28 && u.pm >= 29) { const int j = (31 - u.pm) * 4 + (u.pn - 28); u.pm = 32; u.pn = (j < 6) ? j : 8 + (j - 6); }
;         return true;
.LBB0_118:
	s_ashr_i32 s6, s13, 3
	s_add_i32 s6, s17, s6
	s_ashr_i32 s7, s6, 31
	s_lshr_b32 s7, s7, 24
	s_add_i32 s7, s6, s7
	s_ashr_i32 s13, s7, 8
	s_lshl_b32 s13, s13, 3
	s_sub_i32 s16, 32, s13
	s_min_i32 s16, s16, 8
	s_abs_i32 s17, s16
	v_cvt_f32_u32_e32 v0, s17
	s_sub_i32 s19, 0, s17
	s_and_b32 s7, s7, 0xffffff00
	s_sub_i32 s6, s6, s7
	v_rcp_iflag_f32_e32 v0, v0
	s_abs_i32 s7, s6
	s_xor_b32 s18, s6, s16
	s_ashr_i32 s18, s18, 31
	v_mul_f32_e32 v0, 0x4f7ffffe, v0
	v_cvt_u32_f32_e32 v0, v0
	s_nop 0
	v_readfirstlane_b32 s20, v0
	s_mul_i32 s19, s19, s20
	s_mul_hi_u32 s19, s20, s19
	s_add_i32 s20, s20, s19
	s_mul_hi_u32 s19, s7, s20
	s_mul_i32 s20, s19, s17
	s_sub_i32 s7, s7, s20
	s_add_i32 s21, s19, 1
	s_sub_i32 s20, s7, s17
	s_cmp_ge_u32 s7, s17
	s_cselect_b32 s19, s21, s19
	s_cselect_b32 s7, s20, s7
	s_add_i32 s20, s19, 1
	s_cmp_ge_u32 s7, s17
	s_cselect_b32 s7, s20, s19
	s_xor_b32 s7, s7, s18
	s_sub_i32 s18, s7, s18
	s_mul_i32 s7, s18, s16
	s_sub_i32 s6, s6, s7
	s_add_i32 s13, s13, s6
	s_lshr_b32 s6, s18, 2
	s_lshr_b32 s7, s18, 4
	s_xor_b32 s6, s6, s7
	s_and_b32 s6, s6, 1
	s_mul_i32 s6, s6, 20
	s_xor_b32 s18, s18, s6
	s_cmp_gt_i32 s18, 27
	s_cselect_b64 s[6:7], -1, 0
	s_cmp_gt_i32 s13, 28
	s_cselect_b64 s[16:17], -1, 0
	s_and_b64 s[6:7], s[6:7], s[16:17]
	s_lshl_b32 s16, s13, 2
	s_sub_i32 s16, s18, s16
	s_cmpk_lt_i32 s16, 0xffa6
	s_movk_i32 s17, 0x60
	s_cselect_b32 s17, s17, 0x62
	s_add_i32 s17, s17, s16
	s_and_b64 s[6:7], s[6:7], exec
	s_cselect_b32 s46, s17, s18
	s_cselect_b32 s48, 32, s13
